# hand-written epilogue for the mixproj/XQ GEMM instance (plain columns, rsl path): rstd reads hoisted, no per-group branches, packed scale + cvt + 2 stores per row group
# baseline (speedup 1.0000x reference)
; __device__ __forceinline__ unsigned cvt_pk_bf16(float lo, float hi) { unsigned r; asm volatile("v_cvt_pk_bf16_f32 %0, %1, %2" : "=v"(r) : "v"(lo), "v"(hi)); return r; }
;     __device__ __forceinline__ void operator()(const f32x4 (&acc)[2][2][4][2], const Unit& u, int wr, int wc, int fr, int fq) const {
;     ...
; #pragma unroll
;         for (int ai = 0; ai < 2; ++ai)
; #pragma unroll
;             for (int m = 0; m < 4; ++m) { const int row = row0 + ai * HALF + m * 16; bf16_t* rowp = O + (size_t)row * ldc + col0;
;                 float sc = 1.f; if (SCALE) sc = rsl ? rsl[((u.pm - pm0) >> 3) * 256 + (row & 255)] : row_rstd(ssq, row);
; #pragma unroll
;                 for (int bj = 0; bj < 2; ++bj) { f32x4 v0 = acc[ai][bj][m][0] * sc, v1 = acc[ai][bj][m][1] * sc;
;                     if (ACT == 1) {
; #pragma unroll
;                         for (int j = 0; j < 4; ++j) { const float a = __builtin_fmaxf(v0[j], 0.f), b = __builtin_fmaxf(v1[j], 0.f); v0[j] = a * a; v1[j] = b * b; } }
;                     u32x4 w; w.x = cvt_pk_bf16(v0[0], v0[1]); w.y = cvt_pk_bf16(v0[2], v0[3]); w.z = cvt_pk_bf16(v1[0], v1[1]); w.w = cvt_pk_bf16(v1[2], v1[3]);
;                     __builtin_nontemporal_store(w, (u32x4*)(rowp + bj * HALF)); } }
.LBB0_512:
	s_and_b64 vcc, exec, s[76:77]
	s_cbranch_vccz .LBB0_580
	v_ashrrev_i32_e32 v143, 31, v142
	s_and_b64 vcc, exec, s[60:61]
	s_cbranch_vccnz .Lmpe_slow
	s_sub_i32 s67, s6, s20
	s_lshl_b32 s67, s67, 7
	s_and_b32 s67, s67, 0xfffffc00
	v_add_u32_e32 v0, s67, v150
	ds_read_b32 v226, v0 offset:0
	ds_read_b32 v228, v0 offset:64
	ds_read_b32 v230, v0 offset:128
	ds_read_b32 v232, v0 offset:192
	ds_read_b32 v234, v0 offset:512
	ds_read_b32 v236, v0 offset:576
	ds_read_b32 v238, v0 offset:640
	ds_read_b32 v240, v0 offset:704
	v_lshl_or_b32 v144, s74, 8, v151
	v_ashrrev_i32_e32 v145, 31, v144
	v_mul_lo_u32 v154, v142, s54
	v_mov_b32_e32 v155, 0
	v_lshl_add_u64 v[154:155], v[154:155], 1, s[52:53]
	v_lshl_add_u64 v[154:155], v[144:145], 1, v[154:155]
	s_lshl_b32 s74, s54, 5
	s_lshl_b32 s75, s54, 8
	s_waitcnt lgkmcnt(7)
	v_mov_b32_e32 v156, v154
	v_mov_b32_e32 v157, v155
	v_pk_mul_f32 v[114:115], v[114:115], v[226:227] op_sel_hi:[1,0]
	v_pk_mul_f32 v[116:117], v[116:117], v[226:227] op_sel_hi:[1,0]
	v_pk_mul_f32 v[118:119], v[118:119], v[226:227] op_sel_hi:[1,0]
	v_pk_mul_f32 v[120:121], v[120:121], v[226:227] op_sel_hi:[1,0]
	v_pk_mul_f32 v[122:123], v[122:123], v[226:227] op_sel_hi:[1,0]
	v_pk_mul_f32 v[124:125], v[124:125], v[226:227] op_sel_hi:[1,0]
	v_pk_mul_f32 v[126:127], v[126:127], v[226:227] op_sel_hi:[1,0]
	v_pk_mul_f32 v[128:129], v[128:129], v[226:227] op_sel_hi:[1,0]
	v_cvt_pk_bf16_f32 v158, v126, v127
	v_cvt_pk_bf16_f32 v159, v128, v129
	v_cvt_pk_bf16_f32 v160, v122, v123
	v_cvt_pk_bf16_f32 v161, v124, v125
	global_store_dwordx4 v[156:157], v[158:161], off nt
	v_cvt_pk_bf16_f32 v162, v118, v119
	v_cvt_pk_bf16_f32 v163, v120, v121
	v_cvt_pk_bf16_f32 v164, v114, v115
	v_cvt_pk_bf16_f32 v165, v116, v117
	global_store_dwordx4 v[156:157], v[162:165], off offset:256 nt
	s_waitcnt lgkmcnt(6)
	v_add_co_u32_e32 v156, vcc, s74, v156
	v_addc_co_u32_e32 v157, vcc, 0, v157, vcc
	v_pk_mul_f32 v[98:99], v[98:99], v[228:229] op_sel_hi:[1,0]
	v_pk_mul_f32 v[100:101], v[100:101], v[228:229] op_sel_hi:[1,0]
	v_pk_mul_f32 v[102:103], v[102:103], v[228:229] op_sel_hi:[1,0]
	v_pk_mul_f32 v[104:105], v[104:105], v[228:229] op_sel_hi:[1,0]
	v_pk_mul_f32 v[106:107], v[106:107], v[228:229] op_sel_hi:[1,0]
	v_pk_mul_f32 v[108:109], v[108:109], v[228:229] op_sel_hi:[1,0]
	v_pk_mul_f32 v[110:111], v[110:111], v[228:229] op_sel_hi:[1,0]
	v_pk_mul_f32 v[112:113], v[112:113], v[228:229] op_sel_hi:[1,0]
	v_cvt_pk_bf16_f32 v166, v110, v111
	v_cvt_pk_bf16_f32 v167, v112, v113
	v_cvt_pk_bf16_f32 v168, v106, v107
	v_cvt_pk_bf16_f32 v169, v108, v109
	global_store_dwordx4 v[156:157], v[166:169], off nt
	v_cvt_pk_bf16_f32 v170, v102, v103
	v_cvt_pk_bf16_f32 v171, v104, v105
	v_cvt_pk_bf16_f32 v172, v98, v99
	v_cvt_pk_bf16_f32 v173, v100, v101
	global_store_dwordx4 v[156:157], v[170:173], off offset:256 nt
	s_waitcnt lgkmcnt(5)
	v_add_co_u32_e32 v156, vcc, s74, v156
	v_addc_co_u32_e32 v157, vcc, 0, v157, vcc
	v_pk_mul_f32 v[82:83], v[82:83], v[230:231] op_sel_hi:[1,0]
	v_pk_mul_f32 v[84:85], v[84:85], v[230:231] op_sel_hi:[1,0]
	v_pk_mul_f32 v[86:87], v[86:87], v[230:231] op_sel_hi:[1,0]
	v_pk_mul_f32 v[88:89], v[88:89], v[230:231] op_sel_hi:[1,0]
	v_pk_mul_f32 v[90:91], v[90:91], v[230:231] op_sel_hi:[1,0]
	v_pk_mul_f32 v[92:93], v[92:93], v[230:231] op_sel_hi:[1,0]
	v_pk_mul_f32 v[94:95], v[94:95], v[230:231] op_sel_hi:[1,0]
	v_pk_mul_f32 v[96:97], v[96:97], v[230:231] op_sel_hi:[1,0]
	v_cvt_pk_bf16_f32 v158, v94, v95
	v_cvt_pk_bf16_f32 v159, v96, v97
	v_cvt_pk_bf16_f32 v160, v90, v91
	v_cvt_pk_bf16_f32 v161, v92, v93
	global_store_dwordx4 v[156:157], v[158:161], off nt
	v_cvt_pk_bf16_f32 v162, v86, v87
	v_cvt_pk_bf16_f32 v163, v88, v89
	v_cvt_pk_bf16_f32 v164, v82, v83
	v_cvt_pk_bf16_f32 v165, v84, v85
	global_store_dwordx4 v[156:157], v[162:165], off offset:256 nt
	s_waitcnt lgkmcnt(4)
	v_add_co_u32_e32 v156, vcc, s74, v156
	v_addc_co_u32_e32 v157, vcc, 0, v157, vcc
	v_pk_mul_f32 v[66:67], v[66:67], v[232:233] op_sel_hi:[1,0]
	v_pk_mul_f32 v[68:69], v[68:69], v[232:233] op_sel_hi:[1,0]
	v_pk_mul_f32 v[70:71], v[70:71], v[232:233] op_sel_hi:[1,0]
	v_pk_mul_f32 v[72:73], v[72:73], v[232:233] op_sel_hi:[1,0]
	v_pk_mul_f32 v[74:75], v[74:75], v[232:233] op_sel_hi:[1,0]
	v_pk_mul_f32 v[76:77], v[76:77], v[232:233] op_sel_hi:[1,0]
	v_pk_mul_f32 v[78:79], v[78:79], v[232:233] op_sel_hi:[1,0]
	v_pk_mul_f32 v[80:81], v[80:81], v[232:233] op_sel_hi:[1,0]
	v_cvt_pk_bf16_f32 v166, v78, v79
	v_cvt_pk_bf16_f32 v167, v80, v81
	v_cvt_pk_bf16_f32 v168, v74, v75
	v_cvt_pk_bf16_f32 v169, v76, v77
	global_store_dwordx4 v[156:157], v[166:169], off nt
	v_cvt_pk_bf16_f32 v170, v70, v71
	v_cvt_pk_bf16_f32 v171, v72, v73
	v_cvt_pk_bf16_f32 v172, v66, v67
	v_cvt_pk_bf16_f32 v173, v68, v69
	global_store_dwordx4 v[156:157], v[170:173], off offset:256 nt
	s_waitcnt lgkmcnt(3)
; __device__ __forceinline__ unsigned cvt_pk_bf16(float lo, float hi) { unsigned r; asm volatile("v_cvt_pk_bf16_f32 %0, %1, %2" : "=v"(r) : "v"(lo), "v"(hi)); return r; }
; __device__ __forceinline__ float row_rstd(const float* ssq, int row) {
;     const f32x4* p = (const f32x4*)(ssq + (size_t)row * 16);
;     const f32x4 a = p[0], b = p[1], c = p[2], d = p[3];
;     const float s = (((a[0] + a[1]) + (a[2] + a[3])) + ((b[0] + b[1]) + (b[2] + b[3]))) + (((c[0] + c[1]) + (c[2] + c[3])) + ((d[0] + d[1]) + (d[2] + d[3])));
;     return __builtin_amdgcn_rsqf(s * (1.0f / 1024.0f) + 1e-6f);
; }
;     __device__ __forceinline__ void operator()(const f32x4 (&acc)[2][2][4][2], const Unit& u, int wr, int wc, int fr, int fq) const {
;     ...
; #pragma unroll
;         for (int ai = 0; ai < 2; ++ai)
; #pragma unroll
;             for (int m = 0; m < 4; ++m) { const int row = row0 + ai * HALF + m * 16; bf16_t* rowp = O + (size_t)row * ldc + col0;
;                 float sc = 1.f; if (SCALE) sc = rsl ? rsl[((u.pm - pm0) >> 3) * 256 + (row & 255)] : row_rstd(ssq, row);
; #pragma unroll
;                 for (int bj = 0; bj < 2; ++bj) { f32x4 v0 = acc[ai][bj][m][0] * sc, v1 = acc[ai][bj][m][1] * sc;
;                     if (ACT == 1) {
; #pragma unroll
;                         for (int j = 0; j < 4; ++j) { const float a = __builtin_fmaxf(v0[j], 0.f), b = __builtin_fmaxf(v1[j], 0.f); v0[j] = a * a; v1[j] = b * b; } }
;                     u32x4 w; w.x = cvt_pk_bf16(v0[0], v0[1]); w.y = cvt_pk_bf16(v0[2], v0[3]); w.z = cvt_pk_bf16(v1[0], v1[1]); w.w = cvt_pk_bf16(v1[2], v1[3]);
;                     __builtin_nontemporal_store(w, (u32x4*)(rowp + bj * HALF)); } }
	v_add_co_u32_e32 v156, vcc, s75, v154
	v_addc_co_u32_e32 v157, vcc, 0, v155, vcc
	v_pk_mul_f32 v[50:51], v[50:51], v[234:235] op_sel_hi:[1,0]
	v_pk_mul_f32 v[52:53], v[52:53], v[234:235] op_sel_hi:[1,0]
	v_pk_mul_f32 v[54:55], v[54:55], v[234:235] op_sel_hi:[1,0]
	v_pk_mul_f32 v[56:57], v[56:57], v[234:235] op_sel_hi:[1,0]
	v_pk_mul_f32 v[58:59], v[58:59], v[234:235] op_sel_hi:[1,0]
	v_pk_mul_f32 v[60:61], v[60:61], v[234:235] op_sel_hi:[1,0]
	v_pk_mul_f32 v[62:63], v[62:63], v[234:235] op_sel_hi:[1,0]
	v_pk_mul_f32 v[64:65], v[64:65], v[234:235] op_sel_hi:[1,0]
	v_cvt_pk_bf16_f32 v158, v62, v63
	v_cvt_pk_bf16_f32 v159, v64, v65
	v_cvt_pk_bf16_f32 v160, v58, v59
	v_cvt_pk_bf16_f32 v161, v60, v61
	global_store_dwordx4 v[156:157], v[158:161], off nt
	v_cvt_pk_bf16_f32 v162, v54, v55
	v_cvt_pk_bf16_f32 v163, v56, v57
	v_cvt_pk_bf16_f32 v164, v50, v51
	v_cvt_pk_bf16_f32 v165, v52, v53
	global_store_dwordx4 v[156:157], v[162:165], off offset:256 nt
	s_waitcnt lgkmcnt(2)
	v_add_co_u32_e32 v156, vcc, s74, v156
	v_addc_co_u32_e32 v157, vcc, 0, v157, vcc
	v_pk_mul_f32 v[34:35], v[34:35], v[236:237] op_sel_hi:[1,0]
	v_pk_mul_f32 v[36:37], v[36:37], v[236:237] op_sel_hi:[1,0]
	v_pk_mul_f32 v[38:39], v[38:39], v[236:237] op_sel_hi:[1,0]
	v_pk_mul_f32 v[40:41], v[40:41], v[236:237] op_sel_hi:[1,0]
	v_pk_mul_f32 v[42:43], v[42:43], v[236:237] op_sel_hi:[1,0]
	v_pk_mul_f32 v[44:45], v[44:45], v[236:237] op_sel_hi:[1,0]
	v_pk_mul_f32 v[46:47], v[46:47], v[236:237] op_sel_hi:[1,0]
	v_pk_mul_f32 v[48:49], v[48:49], v[236:237] op_sel_hi:[1,0]
	v_cvt_pk_bf16_f32 v166, v46, v47
	v_cvt_pk_bf16_f32 v167, v48, v49
	v_cvt_pk_bf16_f32 v168, v42, v43
	v_cvt_pk_bf16_f32 v169, v44, v45
	global_store_dwordx4 v[156:157], v[166:169], off nt
	v_cvt_pk_bf16_f32 v170, v38, v39
	v_cvt_pk_bf16_f32 v171, v40, v41
	v_cvt_pk_bf16_f32 v172, v34, v35
	v_cvt_pk_bf16_f32 v173, v36, v37
	global_store_dwordx4 v[156:157], v[170:173], off offset:256 nt
	s_waitcnt lgkmcnt(1)
	v_add_co_u32_e32 v156, vcc, s74, v156
	v_addc_co_u32_e32 v157, vcc, 0, v157, vcc
	v_pk_mul_f32 v[18:19], v[18:19], v[238:239] op_sel_hi:[1,0]
	v_pk_mul_f32 v[20:21], v[20:21], v[238:239] op_sel_hi:[1,0]
	v_pk_mul_f32 v[22:23], v[22:23], v[238:239] op_sel_hi:[1,0]
	v_pk_mul_f32 v[24:25], v[24:25], v[238:239] op_sel_hi:[1,0]
	v_pk_mul_f32 v[26:27], v[26:27], v[238:239] op_sel_hi:[1,0]
	v_pk_mul_f32 v[28:29], v[28:29], v[238:239] op_sel_hi:[1,0]
	v_pk_mul_f32 v[30:31], v[30:31], v[238:239] op_sel_hi:[1,0]
	v_pk_mul_f32 v[32:33], v[32:33], v[238:239] op_sel_hi:[1,0]
	v_cvt_pk_bf16_f32 v158, v30, v31
	v_cvt_pk_bf16_f32 v159, v32, v33
	v_cvt_pk_bf16_f32 v160, v26, v27
	v_cvt_pk_bf16_f32 v161, v28, v29
	global_store_dwordx4 v[156:157], v[158:161], off nt
	v_cvt_pk_bf16_f32 v162, v22, v23
	v_cvt_pk_bf16_f32 v163, v24, v25
	v_cvt_pk_bf16_f32 v164, v18, v19
	v_cvt_pk_bf16_f32 v165, v20, v21
	global_store_dwordx4 v[156:157], v[162:165], off offset:256 nt
	s_waitcnt lgkmcnt(0)
	v_add_co_u32_e32 v156, vcc, s74, v156
	v_addc_co_u32_e32 v157, vcc, 0, v157, vcc
	v_pk_mul_f32 v[2:3], v[2:3], v[240:241] op_sel_hi:[1,0]
	v_pk_mul_f32 v[4:5], v[4:5], v[240:241] op_sel_hi:[1,0]
	v_pk_mul_f32 v[6:7], v[6:7], v[240:241] op_sel_hi:[1,0]
	v_pk_mul_f32 v[8:9], v[8:9], v[240:241] op_sel_hi:[1,0]
	v_pk_mul_f32 v[10:11], v[10:11], v[240:241] op_sel_hi:[1,0]
	v_pk_mul_f32 v[12:13], v[12:13], v[240:241] op_sel_hi:[1,0]
	v_pk_mul_f32 v[14:15], v[14:15], v[240:241] op_sel_hi:[1,0]
	v_pk_mul_f32 v[16:17], v[16:17], v[240:241] op_sel_hi:[1,0]
	v_cvt_pk_bf16_f32 v166, v14, v15
	v_cvt_pk_bf16_f32 v167, v16, v17
	v_cvt_pk_bf16_f32 v168, v10, v11
	v_cvt_pk_bf16_f32 v169, v12, v13
	global_store_dwordx4 v[156:157], v[166:169], off nt
	v_cvt_pk_bf16_f32 v170, v6, v7
	v_cvt_pk_bf16_f32 v171, v8, v9
	v_cvt_pk_bf16_f32 v172, v2, v3
	v_cvt_pk_bf16_f32 v173, v4, v5
	global_store_dwordx4 v[156:157], v[170:173], off offset:256 nt
	s_branch .LBB0_580
.Lmpe_slow:
	s_mov_b64 s[76:77], -1
	s_and_b64 vcc, exec, s[60:61]
	s_cbranch_vccz .LBB0_515
	v_lshlrev_b64 v[144:145], 6, v[142:143]
	v_lshl_add_u64 v[144:145], s[56:57], 0, v[144:145]
	global_load_dwordx4 v[154:157], v[144:145], off
	global_load_dwordx4 v[158:161], v[144:145], off offset:32
	global_load_dwordx4 v[162:165], v[144:145], off offset:16
	global_load_dwordx4 v[166:169], v[144:145], off offset:48
	s_mov_b64 s[76:77], 0
	s_waitcnt vmcnt(0)
	v_mov_b32_e32 v144, v154
	v_mov_b32_e32 v145, v158
	v_mov_b32_e32 v158, v155
	v_mov_b32_e32 v154, v156
	v_mov_b32_e32 v155, v160
	v_mov_b32_e32 v160, v157
	v_mov_b32_e32 v156, v162
	v_mov_b32_e32 v157, v166
	v_mov_b32_e32 v166, v163
	v_mov_b32_e32 v162, v164
	v_mov_b32_e32 v163, v168
	v_mov_b32_e32 v168, v165
	v_pk_add_f32 v[144:145], v[144:145], v[158:159]
	v_pk_add_f32 v[154:155], v[154:155], v[160:161]
	v_pk_add_f32 v[156:157], v[156:157], v[166:167]
	v_pk_add_f32 v[158:159], v[162:163], v[168:169]
	v_pk_add_f32 v[144:145], v[144:145], v[154:155]
	v_pk_add_f32 v[154:155], v[156:157], v[158:159]
	s_nop 0
	v_pk_add_f32 v[144:145], v[144:145], v[154:155]
	s_nop 0
	v_add_f32_e32 v0, v144, v145
	v_fmamk_f32 v0, v0, 0x3a800000, v207
	v_rsq_f32_e32 v0, v0
